# mixer: 96 workgroups dedicated to the deferred conversions from phase start (unthrottled), attention on the remaining 352
# speedup vs baseline: 1.0092x; 1.0092x over previous
; __device__ __forceinline__ int tid_() { int t = threadIdx.x; asm volatile("" : "+v"(t)); return t; }
; __device__ void ph_mixer(const P& p, u16* lds) {
;   const int NSCAN = 32;
;     ...
;   if ((int)blockIdx.x < NSCAN) { if (MIXMASK & 1) scan_seq(p, blockIdx.x, lds); return; }
;   const int NA = 2048, NSA = 256, NSD = 256, NCP = 2409;
;   const int st = gridDim.x - NSCAN, b0 = blockIdx.x - NSCAN;
;   auto first = [&](int off) { int f = b0 - (off % st); return f < 0 ? f + st : f; };
;   if (MIXMASK & 8) for (int it = first(0); it < NSD; it += st) dn_sample_wave(p, it * 4 + (tid_() >> 6));
;   if (MIXMASK & 4) for (int it = first(224); it < NSA; it += st) attn_sample_item(p, it, lds);
;   if (MIXMASK & 2) for (int it = first(288); it < NA; it += st) attn_prompt_item(p, it, lds);
;   if (MIXMASK & 16) for (int it = first(256); it < NCP; it += st) copy_item(p, it);
; }
.LBB0_300:
	s_cmp_lt_i32 s6, 4
	s_cselect_b64 s[0:1], -1, 0
	s_cmp_gt_i32 s7, 3
	s_cselect_b64 s[2:3], -1, 0
	s_and_b64 s[0:1], s[0:1], s[2:3]
	s_andn2_b64 vcc, exec, s[0:1]
	s_cbranch_vccnz .LBB0_539
	v_readlane_b32 s2, v228, 0
	v_readlane_b32 s0, v228, 10
	s_nop 1
	v_writelane_b32 v227, s2, 60
	v_writelane_b32 v227, s0, 61
	v_writelane_b32 v227, 0, 62
	s_cmp_gt_i32 s2, 31
	s_mov_b64 s[0:1], -1
	v_readlane_b32 s3, v228, 1
	s_cbranch_scc0 .LBB0_478
	v_readlane_b32 s0, v228, 10
	s_nop 1
	s_cmpk_lg_u32 s0, 0x200
	s_cbranch_scc1 .Lmx_orig
	s_cmpk_lt_u32 s2, 0x100
	s_cbranch_scc1 .Lmx_keep
	s_cmpk_lt_u32 s2, 0x120
	s_cbranch_scc1 .LBB0_485
	s_sub_i32 s2, s2, 32
.Lmx_keep:
	s_cmpk_lt_u32 s2, 0x80
	s_cbranch_scc1 .Lmx_conv
	s_sub_i32 s2, s2, 0x60
	v_readlane_b32 s0, v228, 10
	s_nop 1
	s_sub_i32 s0, s0, 0x80
	s_mov_b32 s1, 1
	s_nop 1
	v_writelane_b32 v228, s2, 0
	v_writelane_b32 v228, s0, 10
	v_writelane_b32 v227, s1, 62
	s_nop 1
	s_branch .Lmx_orig
.Lmx_conv:
	s_movk_i32 s0, 0x80
	s_nop 1
	v_writelane_b32 v228, s0, 10
	s_nop 1
	s_branch .Ldef_entry

; __device__ __forceinline__ int tid_() { int t = threadIdx.x; asm volatile("" : "+v"(t)); return t; }
; __device__ __forceinline__ void conv_table_chunk4(const float* __restrict__ src, unsigned char* __restrict__ dst, size_t base, float scale) {
;   f32x4 a[4], b[4];
; #pragma unroll
;   for (int q = 0; q < 4; ++q) {
;     size_t i = base + (size_t)q * 2048 + (size_t)tid_() * 8;
;     a[q] = *(const f32x4*)(src + i); b[q] = *(const f32x4*)(src + i + 4);
;   }
; #pragma unroll
;   for (int q = 0; q < 4; ++q) {
;     size_t i = base + (size_t)q * 2048 + (size_t)tid_() * 8;
;     int w0 = 0, w1 = 0;
;     w0 = __builtin_amdgcn_cvt_pk_fp8_f32(a[q][0] * scale, a[q][1] * scale, w0, false);
;     w0 = __builtin_amdgcn_cvt_pk_fp8_f32(a[q][2] * scale, a[q][3] * scale, w0, true);
;     w1 = __builtin_amdgcn_cvt_pk_fp8_f32(b[q][0] * scale, b[q][1] * scale, w1, false);
;     w1 = __builtin_amdgcn_cvt_pk_fp8_f32(b[q][2] * scale, b[q][3] * scale, w1, true);
;     size_t e = i >> 10; int col = (int)(i & 1023); int x = col >> 7;
;     *(uint2*)(dst + ((size_t)x * 16384 + e) * 128 + (col & 127)) = make_uint2((unsigned)w0, (unsigned)w1);
; __device__ void ph_mixer(const P& p, u16* lds) {
;   const int NSCAN = 32;
;     ...
;   if ((int)blockIdx.x < NSCAN) { if (MIXMASK & 1) scan_seq(p, blockIdx.x, lds); return; }
;   const int NA = 2048, NSA = 256, NSD = 256, NCP = 2409;
;   const int st = gridDim.x - NSCAN, b0 = blockIdx.x - NSCAN;
;   auto first = [&](int off) { int f = b0 - (off % st); return f < 0 ? f + st : f; };
;   if (MIXMASK & 8) for (int it = first(0); it < NSD; it += st) dn_sample_wave(p, it * 4 + (tid_() >> 6));
;   if (MIXMASK & 4) for (int it = first(224); it < NSA; it += st) attn_sample_item(p, it, lds);
;   if (MIXMASK & 2) for (int it = first(288); it < NA; it += st) attn_prompt_item(p, it, lds);
;   if (MIXMASK & 16) for (int it = first(256); it < NCP; it += st) copy_item(p, it);
.Ldef_entry:
	v_readlane_b32 s52, v227, 62
	s_cmp_eq_u32 s52, 1
	s_cbranch_scc1 .Ldef_done
	v_readlane_b32 s50, v228, 0
	v_readlane_b32 s51, v228, 10
	v_readlane_b32 s40, v228, 8
	v_readlane_b32 s41, v228, 9
	v_readlane_b32 s42, v228, 57
	v_readlane_b32 s43, v228, 58
	v_readlane_b32 s44, v228, 59
	v_readlane_b32 s45, v228, 60
	v_readlane_b32 s46, v228, 21
	v_readlane_b32 s47, v228, 22
	v_readlane_b32 s48, v228, 23
	v_readlane_b32 s49, v228, 24
	s_sub_u32 s50, s50, 32
	s_sub_u32 s51, s51, 32
	v_lshlrev_b32_e32 v1, 5, v220
	v_add_u32_e32 v5, 0x2000, v1
	v_add_u32_e32 v6, 0x4000, v1
	v_add_u32_e32 v7, 0x6000, v1
	v_lshlrev_b32_e32 v3, 4, v220
	v_add_u32_e32 v9, 0x1000, v3
	v_add_u32_e32 v10, 0x2000, v3
	v_add_u32_e32 v11, 0x3000, v3
	v_bfe_u32 v2, v220, 4, 3
	v_lshlrev_b32_e32 v2, 21, v2
	v_lshrrev_b32_e32 v12, 7, v220
	v_lshl_or_b32 v2, v12, 7, v2
	v_and_b32_e32 v12, 15, v220
	v_lshl_or_b32 v2, v12, 3, v2
	v_mov_b32_e32 v13, 0
